# g2_loader_waits_relaxed_vmcnt22_plus_xcd_first_seam
# speedup vs baseline: 1.0114x; 1.0029x over previous
.LBB0_1970:
	s_cmpk_lg_i32 s73, 0xff
	s_cselect_b64 s[4:5], -1, 0
	s_cmpk_eq_i32 s73, 0xff
	s_cbranch_scc1 .LBB0_1974
	s_andn2_b32 s38, 1, s73
	v_lshl_add_u32 v130, s38, 16, v125
	s_cmpk_lt_u32 s73, 0xf0
	s_cbranch_scc0 .Lg2st_orig_1
	s_waitcnt vmcnt(22)
	ds_write_b128 v130, v[0:3]
	ds_write_b128 v130, v[4:7] offset:6144
	ds_write_b128 v130, v[8:11] offset:12288
	ds_write_b128 v130, v[12:15] offset:18432
	ds_write_b128 v130, v[20:23] offset:24576
	ds_write_b128 v130, v[24:27] offset:30720
	ds_write_b128 v130, v[32:35] offset:36864
	ds_write_b128 v130, v[36:39] offset:43008
	ds_write_b128 v130, v[40:43] offset:49152
	ds_write_b128 v130, v[48:51] offset:55296
	s_branch .Lg2st_done_1
.Lg2st_orig_1:
	s_waitcnt vmcnt(10)
	ds_write_b128 v130, v[0:3]
	s_waitcnt vmcnt(9)
	ds_write_b128 v130, v[4:7] offset:6144
	s_waitcnt vmcnt(8)
	ds_write_b128 v130, v[8:11] offset:12288
	s_waitcnt vmcnt(7)
	ds_write_b128 v130, v[12:15] offset:18432
	s_waitcnt vmcnt(6)
	ds_write_b128 v130, v[20:23] offset:24576
	s_waitcnt vmcnt(5)
	ds_write_b128 v130, v[24:27] offset:30720
	s_waitcnt vmcnt(4)
	ds_write_b128 v130, v[32:35] offset:36864
	s_waitcnt vmcnt(3)
	ds_write_b128 v130, v[36:39] offset:43008
	s_waitcnt vmcnt(2)
	ds_write_b128 v130, v[40:43] offset:49152
	s_waitcnt vmcnt(1)
	ds_write_b128 v130, v[48:51] offset:55296
.Lg2st_done_1:
	s_and_saveexec_b64 s[0:1], s[6:7]
	s_cbranch_execz .LBB0_1973
	s_lshl_b32 s38, s38, 2
	s_add_i32 s38, s38, 0
	s_add_i32 s38, s38, 0x20000
	v_mov_b32_e32 v130, s38
	s_cmpk_lt_u32 s73, 0xf0
	s_cbranch_scc1 .Lg2cd_skip_1
	s_waitcnt vmcnt(0)
.Lg2cd_skip_1:
	ds_write_b32 v130, v127

.LBB0_2011:
	v_lshl_add_u64 v[0:1], s[62:63], 0, v[120:121]
	global_load_dwordx4 v[0:3], v[0:1], off
	s_and_b64 vcc, exec, s[8:9]
	s_mov_b64 s[0:1], -1
	s_cbranch_vccnz .LBB0_2025
	s_and_b64 vcc, exec, s[10:11]
	s_cbranch_vccnz .LBB0_2022
	s_andn2_b64 vcc, exec, s[56:57]
	s_cbranch_vccnz .LBB0_2019
	v_readlane_b32 s0, v253, 30
	v_readlane_b32 s1, v253, 31
	s_andn2_b64 vcc, exec, s[0:1]
	s_mov_b64 s[0:1], -1
	s_cbranch_vccnz .LBB0_2016
	v_readlane_b32 s0, v253, 33
	s_add_u32 s62, s58, s0
	s_addc_u32 s63, s80, 0
	s_mov_b64 s[0:1], 0

.LBB0_2027:
	v_lshl_add_u64 v[4:5], s[62:63], 0, v[120:121]
	global_load_dwordx4 v[4:7], v[4:5], off
	s_and_b64 vcc, exec, s[12:13]
	s_mov_b64 s[0:1], -1
	s_cbranch_vccnz .LBB0_2041
	s_and_b64 vcc, exec, s[14:15]
	s_cbranch_vccnz .LBB0_2038
	s_andn2_b64 vcc, exec, s[64:65]
	s_cbranch_vccnz .LBB0_2035
	v_readlane_b32 s0, v253, 39
	v_readlane_b32 s1, v253, 40
	s_andn2_b64 vcc, exec, s[0:1]
	s_mov_b64 s[0:1], -1
	s_cbranch_vccnz .LBB0_2032
	v_readlane_b32 s0, v253, 41
	s_add_u32 s62, s58, s0
	s_addc_u32 s63, s80, 0
	s_mov_b64 s[0:1], 0

.LBB0_2043:
	v_lshl_add_u64 v[8:9], s[62:63], 0, v[120:121]
	global_load_dwordx4 v[8:11], v[8:9], off
	s_and_b64 vcc, exec, s[16:17]
	s_mov_b64 s[0:1], -1
	s_cbranch_vccnz .LBB0_2053
	s_and_b64 vcc, exec, s[18:19]
	s_cbranch_vccnz .LBB0_2050
	s_andn2_b64 vcc, exec, s[82:83]
	s_cbranch_vccnz .LBB0_2047
	v_readlane_b32 s0, v253, 47
	s_add_u32 s62, s58, s0
	s_addc_u32 s63, s80, 0
	s_mov_b64 s[0:1], 0

.LBB0_2055:
	v_lshl_add_u64 v[12:13], s[62:63], 0, v[120:121]
	global_load_dwordx4 v[12:15], v[12:13], off
	s_and_b64 vcc, exec, s[20:21]
	s_mov_b64 s[0:1], -1
	s_cbranch_vccnz .LBB0_2065
	s_and_b64 vcc, exec, s[22:23]
	s_cbranch_vccnz .LBB0_2062
	s_andn2_b64 vcc, exec, s[90:91]
	s_cbranch_vccnz .LBB0_2059
	v_readlane_b32 s0, v253, 53
	s_add_u32 s62, s58, s0
	s_addc_u32 s63, s80, 0
	s_mov_b64 s[0:1], 0

.LBB0_2067:
	v_lshl_add_u64 v[20:21], s[62:63], 0, v[120:121]
	global_load_dwordx4 v[20:23], v[20:21], off
	s_and_b64 vcc, exec, s[24:25]
	s_mov_b64 s[0:1], -1
	s_cbranch_vccnz .LBB0_2077
	s_and_b64 vcc, exec, s[26:27]
	s_cbranch_vccnz .LBB0_2074
	s_and_b64 vcc, exec, s[10:11]
	s_cbranch_vccnz .LBB0_2071
	v_readlane_b32 s0, v253, 59
	s_add_u32 s62, s58, s0
	s_addc_u32 s63, s80, 0
	s_mov_b64 s[0:1], 0

.LBB0_2079:
	v_lshl_add_u64 v[24:25], s[62:63], 0, v[120:121]
	global_load_dwordx4 v[24:27], v[24:25], off
	s_and_b64 vcc, exec, s[28:29]
	s_mov_b64 s[0:1], -1
	s_cbranch_vccnz .LBB0_2085
	s_and_b64 vcc, exec, s[14:15]
	s_cbranch_vccnz .LBB0_2082
	s_add_u32 s62, s58, s94
	s_addc_u32 s63, s80, 0
	s_mov_b64 s[0:1], 0

.LBB0_2087:
	v_lshl_add_u64 v[32:33], s[62:63], 0, v[120:121]
	global_load_dwordx4 v[32:35], v[32:33], off
	s_and_b64 vcc, exec, s[30:31]
	s_mov_b64 s[0:1], -1
	s_cbranch_vccnz .LBB0_2093
	s_and_b64 vcc, exec, s[16:17]
	s_cbranch_vccnz .LBB0_2090
	s_add_u32 s62, s58, s36
	s_addc_u32 s63, s80, 0
	s_mov_b64 s[0:1], 0

.LBB0_2095:
	s_add_u32 s0, s81, s37
	s_addc_u32 s1, s66, 0
	s_add_u32 s60, s0, 0xa3f4000
	v_lshl_add_u64 v[36:37], s[62:63], 0, v[120:121]
	s_addc_u32 s62, s1, 0
	s_add_u32 s63, s58, s40
	s_addc_u32 s67, s80, 0
	s_and_b64 s[0:1], s[84:85], exec
	s_cselect_b32 s1, s62, s67
	s_cselect_b32 s0, s60, s63
	v_lshl_add_u64 v[40:41], s[0:1], 0, v[120:121]
	s_add_u32 s0, s81, s41
	s_addc_u32 s1, s66, 0
	s_add_u32 s60, s0, 0xa3f4000
	s_addc_u32 s62, s1, 0
	s_add_u32 s58, s58, s97
	s_addc_u32 s63, s80, 0
	s_and_b64 s[0:1], s[92:93], exec
	s_cselect_b32 s1, s62, s63
	s_cselect_b32 s0, s60, s58
	v_lshl_add_u64 v[48:49], s[0:1], 0, v[120:121]
	s_lshl_b64 s[0:1], s[38:39], 2
	s_add_u32 s0, s54, s0
	s_addc_u32 s1, s55, s1
	global_load_dwordx4 v[36:39], v[36:37], off
	s_nop 0
	global_load_dwordx4 v[40:43], v[40:41], off
	s_nop 0
	global_load_dwordx4 v[48:51], v[48:49], off
	s_nop 0
	global_load_dword v127, v121, s[0:1]
.LBB0_2096:
	s_waitcnt lgkmcnt(0)
	s_andn2_b64 vcc, exec, s[4:5]
	s_barrier
	s_cbranch_vccnz .LBB0_2119
	s_cmpk_gt_u32 s73, 0xfd
	s_cbranch_scc1 .LBB0_2101
	s_and_b32 s4, s73, 1
	v_lshl_add_u32 v130, s4, 16, v125
	s_cmpk_lt_u32 s73, 0xf0
	s_cbranch_scc0 .Lg2st_orig_2
	s_waitcnt vmcnt(22)
	ds_write_b128 v130, v[16:19]
	ds_write_b128 v130, v[28:31] offset:6144
	ds_write_b128 v130, v[44:47] offset:12288
	ds_write_b128 v130, v[52:55] offset:18432
	ds_write_b128 v130, v[60:63] offset:24576
	ds_write_b128 v130, v[64:67] offset:30720
	ds_write_b128 v130, v[72:75] offset:36864
	ds_write_b128 v130, v[76:79] offset:43008
	ds_write_b128 v130, v[80:83] offset:49152
	ds_write_b128 v130, v[88:91] offset:55296
	s_branch .Lg2st_done_2
.Lg2st_orig_2:
	s_waitcnt vmcnt(10)
	ds_write_b128 v130, v[16:19]
	s_waitcnt vmcnt(9)
	ds_write_b128 v130, v[28:31] offset:6144
	s_waitcnt vmcnt(8)
	ds_write_b128 v130, v[44:47] offset:12288
	s_waitcnt vmcnt(7)
	ds_write_b128 v130, v[52:55] offset:18432
	s_waitcnt vmcnt(6)
	ds_write_b128 v130, v[60:63] offset:24576
	s_waitcnt vmcnt(5)
	ds_write_b128 v130, v[64:67] offset:30720
	s_waitcnt vmcnt(4)
	ds_write_b128 v130, v[72:75] offset:36864
	s_waitcnt vmcnt(3)
	ds_write_b128 v130, v[76:79] offset:43008
	s_waitcnt vmcnt(2)
	ds_write_b128 v130, v[80:83] offset:49152
	s_waitcnt vmcnt(1)
	ds_write_b128 v130, v[88:91] offset:55296
.Lg2st_done_2:
	s_and_saveexec_b64 s[0:1], s[6:7]
	s_cbranch_execz .LBB0_2100
	s_lshl_b32 s4, s4, 2
	s_add_i32 s4, s4, 0
	s_add_i32 s4, s4, 0x20000
	v_mov_b32_e32 v130, s4
	s_cmpk_lt_u32 s73, 0xf0
	s_cbranch_scc1 .Lg2cd_skip_2
	s_waitcnt vmcnt(0)
.Lg2cd_skip_2:
	ds_write_b32 v130, v128

.LBB0_2139:
	v_lshl_add_u64 v[16:17], s[4:5], 0, v[120:121]
	global_load_dwordx4 v[16:19], v[16:17], off
	s_and_b64 vcc, exec, s[8:9]
	s_mov_b64 s[0:1], -1
	s_cbranch_vccnz .LBB0_2153
	s_and_b64 vcc, exec, s[10:11]
	s_cbranch_vccnz .LBB0_2150
	s_andn2_b64 vcc, exec, s[56:57]
	s_cbranch_vccnz .LBB0_2147
	v_readlane_b32 s0, v253, 30
	v_readlane_b32 s1, v253, 31
	s_andn2_b64 vcc, exec, s[0:1]
	s_mov_b64 s[0:1], -1
	s_cbranch_vccnz .LBB0_2144
	v_readlane_b32 s0, v253, 33
	s_add_u32 s4, s58, s0
	s_addc_u32 s5, s59, 0
	s_mov_b64 s[0:1], 0

.LBB0_2155:
	v_lshl_add_u64 v[28:29], s[4:5], 0, v[120:121]
	global_load_dwordx4 v[28:31], v[28:29], off
	s_and_b64 vcc, exec, s[12:13]
	s_mov_b64 s[0:1], -1
	s_cbranch_vccnz .LBB0_2169
	s_and_b64 vcc, exec, s[14:15]
	s_cbranch_vccnz .LBB0_2166
	s_andn2_b64 vcc, exec, s[64:65]
	s_cbranch_vccnz .LBB0_2163
	v_readlane_b32 s0, v253, 39
	v_readlane_b32 s1, v253, 40
	s_andn2_b64 vcc, exec, s[0:1]
	s_mov_b64 s[0:1], -1
	s_cbranch_vccnz .LBB0_2160
	v_readlane_b32 s0, v253, 41
	s_add_u32 s4, s58, s0
	s_addc_u32 s5, s59, 0
	s_mov_b64 s[0:1], 0

.LBB0_2171:
	v_lshl_add_u64 v[44:45], s[4:5], 0, v[120:121]
	global_load_dwordx4 v[44:47], v[44:45], off
	s_and_b64 vcc, exec, s[16:17]
	s_mov_b64 s[0:1], -1
	s_cbranch_vccnz .LBB0_2181
	s_and_b64 vcc, exec, s[18:19]
	s_cbranch_vccnz .LBB0_2178
	s_andn2_b64 vcc, exec, s[82:83]
	s_cbranch_vccnz .LBB0_2175
	v_readlane_b32 s0, v253, 47
	s_add_u32 s4, s58, s0
	s_addc_u32 s5, s59, 0
	s_mov_b64 s[0:1], 0

.LBB0_2183:
	v_lshl_add_u64 v[52:53], s[4:5], 0, v[120:121]
	global_load_dwordx4 v[52:55], v[52:53], off
	s_and_b64 vcc, exec, s[20:21]
	s_mov_b64 s[0:1], -1
	s_cbranch_vccnz .LBB0_2193
	s_and_b64 vcc, exec, s[22:23]
	s_cbranch_vccnz .LBB0_2190
	s_andn2_b64 vcc, exec, s[90:91]
	s_cbranch_vccnz .LBB0_2187
	v_readlane_b32 s0, v253, 53
	s_add_u32 s4, s58, s0
	s_addc_u32 s5, s59, 0
	s_mov_b64 s[0:1], 0

.LBB0_2195:
	v_lshl_add_u64 v[60:61], s[4:5], 0, v[120:121]
	global_load_dwordx4 v[60:63], v[60:61], off
	s_and_b64 vcc, exec, s[24:25]
	s_mov_b64 s[0:1], -1
	s_cbranch_vccnz .LBB0_2205
	s_and_b64 vcc, exec, s[26:27]
	s_cbranch_vccnz .LBB0_2202
	s_and_b64 vcc, exec, s[10:11]
	s_cbranch_vccnz .LBB0_2199
	v_readlane_b32 s0, v253, 59
	s_add_u32 s4, s58, s0
	s_addc_u32 s5, s59, 0
	s_mov_b64 s[0:1], 0

.LBB0_2207:
	v_lshl_add_u64 v[64:65], s[4:5], 0, v[120:121]
	global_load_dwordx4 v[64:67], v[64:65], off
	s_and_b64 vcc, exec, s[28:29]
	s_mov_b64 s[0:1], -1
	s_cbranch_vccnz .LBB0_2213
	s_and_b64 vcc, exec, s[14:15]
	s_cbranch_vccnz .LBB0_2210
	s_add_u32 s4, s58, s94
	s_addc_u32 s5, s59, 0
	s_mov_b64 s[0:1], 0

.LBB0_2215:
	v_lshl_add_u64 v[72:73], s[4:5], 0, v[120:121]
	global_load_dwordx4 v[72:75], v[72:73], off
	s_and_b64 vcc, exec, s[30:31]
	s_mov_b64 s[0:1], -1
	s_cbranch_vccnz .LBB0_2221
	s_and_b64 vcc, exec, s[16:17]
	s_cbranch_vccnz .LBB0_2218
	s_add_u32 s4, s58, s36
	s_addc_u32 s5, s59, 0
	s_mov_b64 s[0:1], 0

.LBB0_2223:
	s_add_u32 s0, s62, s37
	s_addc_u32 s1, s63, 0
	v_lshl_add_u64 v[76:77], s[4:5], 0, v[120:121]
	s_add_u32 s4, s0, 0xa3f4000
	s_addc_u32 s5, s1, 0
	s_add_u32 s60, s58, s40
	s_addc_u32 s66, s59, 0
	s_and_b64 s[0:1], s[84:85], exec
	s_cselect_b32 s1, s5, s66
	s_cselect_b32 s0, s4, s60
	v_lshl_add_u64 v[80:81], s[0:1], 0, v[120:121]
	s_add_u32 s0, s62, s41
	s_addc_u32 s1, s63, 0
	s_add_u32 s4, s0, 0xa3f4000
	s_addc_u32 s5, s1, 0
	s_add_u32 s58, s58, s97
	s_addc_u32 s59, s59, 0
	s_and_b64 s[0:1], s[92:93], exec
	s_cselect_b32 s1, s5, s59
	s_cselect_b32 s0, s4, s58
	v_lshl_add_u64 v[88:89], s[0:1], 0, v[120:121]
	s_lshl_b64 s[0:1], s[38:39], 2
	s_add_u32 s0, s54, s0
	s_addc_u32 s1, s55, s1
	global_load_dwordx4 v[76:79], v[76:77], off
	s_nop 0
	global_load_dwordx4 v[80:83], v[80:81], off
	s_nop 0
	global_load_dwordx4 v[88:91], v[88:89], off
	s_nop 0
	global_load_dword v128, v121, s[0:1]

.LBB0_2225:
	s_cmpk_eq_i32 s73, 0xfd
	s_cbranch_scc1 .LBB0_2229
	s_andn2_b32 s4, 1, s73
	v_lshl_add_u32 v130, s4, 16, v125
	s_cmpk_lt_u32 s73, 0xf0
	s_cbranch_scc0 .Lg2st_orig_3
	s_waitcnt vmcnt(22)
	ds_write_b128 v130, v[56:59]
	ds_write_b128 v130, v[68:71] offset:6144
	ds_write_b128 v130, v[84:87] offset:12288
	ds_write_b128 v130, v[92:95] offset:18432
	ds_write_b128 v130, v[96:99] offset:24576
	ds_write_b128 v130, v[100:103] offset:30720
	ds_write_b128 v130, v[104:107] offset:36864
	ds_write_b128 v130, v[108:111] offset:43008
	ds_write_b128 v130, v[112:115] offset:49152
	ds_write_b128 v130, v[116:119] offset:55296
	s_branch .Lg2st_done_3
.Lg2st_orig_3:
	s_waitcnt vmcnt(10)
	ds_write_b128 v130, v[56:59]
	s_waitcnt vmcnt(9)
	ds_write_b128 v130, v[68:71] offset:6144
	s_waitcnt vmcnt(8)
	ds_write_b128 v130, v[84:87] offset:12288
	s_waitcnt vmcnt(7)
	ds_write_b128 v130, v[92:95] offset:18432
	s_waitcnt vmcnt(6)
	ds_write_b128 v130, v[96:99] offset:24576
	s_waitcnt vmcnt(5)
	ds_write_b128 v130, v[100:103] offset:30720
	s_waitcnt vmcnt(4)
	ds_write_b128 v130, v[104:107] offset:36864
	s_waitcnt vmcnt(3)
	ds_write_b128 v130, v[108:111] offset:43008
	s_waitcnt vmcnt(2)
	ds_write_b128 v130, v[112:115] offset:49152
	s_waitcnt vmcnt(1)
	ds_write_b128 v130, v[116:119] offset:55296

.Lg2cd_skip_3:
	ds_write_b32 v130, v129

.LBB0_2264:
	s_andn2_b64 vcc, exec, s[0:1]
	s_cbranch_vccnz .LBB0_2266
	s_add_u32 s4, s68, s96
	s_addc_u32 s5, s80, 0
.LBB0_2266:
	v_lshl_add_u64 v[56:57], s[4:5], 0, v[120:121]
	global_load_dwordx4 v[56:59], v[56:57], off
	s_and_b64 vcc, exec, s[8:9]
	s_mov_b64 s[0:1], -1
	s_cbranch_vccnz .LBB0_2280
	s_and_b64 vcc, exec, s[10:11]
	s_cbranch_vccnz .LBB0_2277
	s_andn2_b64 vcc, exec, s[56:57]
	s_cbranch_vccnz .LBB0_2274
	v_readlane_b32 s0, v253, 30
	v_readlane_b32 s1, v253, 31
	s_andn2_b64 vcc, exec, s[0:1]
	s_mov_b64 s[0:1], -1
	s_cbranch_vccnz .LBB0_2271
	v_readlane_b32 s0, v253, 33
	s_add_u32 s4, s59, s0
	s_addc_u32 s5, s62, 0
	s_mov_b64 s[0:1], 0
.LBB0_2271:
	s_andn2_b64 vcc, exec, s[0:1]
	s_cbranch_vccnz .LBB0_2273
	s_add_u32 s0, s63, s33
	s_addc_u32 s1, s66, 0
	s_add_u32 s4, s0, 0xa3f4000
	s_addc_u32 s5, s1, 0

.LBB0_2280:
	s_andn2_b64 vcc, exec, s[0:1]
	s_cbranch_vccnz .LBB0_2282
	s_add_u32 s4, s68, s33
	s_addc_u32 s5, s80, 0
.LBB0_2282:
	v_lshl_add_u64 v[68:69], s[4:5], 0, v[120:121]
	global_load_dwordx4 v[68:71], v[68:69], off
	s_and_b64 vcc, exec, s[12:13]
	s_mov_b64 s[0:1], -1
	s_cbranch_vccnz .LBB0_2296
	s_and_b64 vcc, exec, s[14:15]
	s_cbranch_vccnz .LBB0_2293
	s_andn2_b64 vcc, exec, s[64:65]
	s_cbranch_vccnz .LBB0_2290
	v_readlane_b32 s0, v253, 39
	v_readlane_b32 s1, v253, 40
	s_andn2_b64 vcc, exec, s[0:1]
	s_mov_b64 s[0:1], -1
	s_cbranch_vccnz .LBB0_2287
	v_readlane_b32 s0, v253, 41
	s_add_u32 s4, s59, s0
	s_addc_u32 s5, s62, 0
	s_mov_b64 s[0:1], 0
.LBB0_2287:
	s_andn2_b64 vcc, exec, s[0:1]
	s_cbranch_vccnz .LBB0_2289
	s_add_u32 s0, s63, s43
	s_addc_u32 s1, s66, 0
	s_add_u32 s4, s0, 0xa3f4000
	s_addc_u32 s5, s1, 0

.LBB0_2296:
	s_andn2_b64 vcc, exec, s[0:1]
	s_cbranch_vccnz .LBB0_2298
	s_add_u32 s4, s68, s43
	s_addc_u32 s5, s80, 0
.LBB0_2298:
	v_lshl_add_u64 v[84:85], s[4:5], 0, v[120:121]
	global_load_dwordx4 v[84:87], v[84:85], off
	s_and_b64 vcc, exec, s[16:17]
	s_mov_b64 s[0:1], -1
	s_cbranch_vccnz .LBB0_2308
	s_and_b64 vcc, exec, s[18:19]
	s_cbranch_vccnz .LBB0_2305
	s_andn2_b64 vcc, exec, s[82:83]
	s_cbranch_vccnz .LBB0_2302
	v_readlane_b32 s0, v253, 47
	s_add_u32 s4, s59, s0
	s_addc_u32 s5, s62, 0
	s_mov_b64 s[0:1], 0
.LBB0_2302:
	s_andn2_b64 vcc, exec, s[0:1]
	s_cbranch_vccnz .LBB0_2304
	s_add_u32 s0, s63, s53
	s_addc_u32 s1, s66, 0
	s_add_u32 s4, s0, 0xa3f4000
	s_addc_u32 s5, s1, 0

.LBB0_2308:
	s_andn2_b64 vcc, exec, s[0:1]
	s_cbranch_vccnz .LBB0_2310
	s_add_u32 s0, s60, s53
	s_addc_u32 s1, s67, 0
	s_add_u32 s4, s0, 0x73fc000
	s_addc_u32 s5, s1, 0
.LBB0_2310:
	v_lshl_add_u64 v[92:93], s[4:5], 0, v[120:121]
	global_load_dwordx4 v[92:95], v[92:93], off
	s_and_b64 vcc, exec, s[20:21]
	s_mov_b64 s[0:1], -1
	s_cbranch_vccnz .LBB0_2320
	s_and_b64 vcc, exec, s[22:23]
	s_cbranch_vccnz .LBB0_2317
	s_andn2_b64 vcc, exec, s[90:91]
	s_cbranch_vccnz .LBB0_2314
	v_readlane_b32 s0, v253, 53
	s_add_u32 s4, s59, s0
	s_addc_u32 s5, s62, 0
	s_mov_b64 s[0:1], 0
.LBB0_2314:
	s_andn2_b64 vcc, exec, s[0:1]
	s_cbranch_vccnz .LBB0_2316
	s_add_u32 s0, s63, s61
	s_addc_u32 s1, s66, 0
	s_add_u32 s4, s0, 0xa3f4000
	s_addc_u32 s5, s1, 0

.LBB0_2320:
	s_andn2_b64 vcc, exec, s[0:1]
	s_cbranch_vccnz .LBB0_2322
	s_add_u32 s0, s60, s61
	s_addc_u32 s1, s67, 0
	s_add_u32 s4, s0, 0x73fc000
	s_addc_u32 s5, s1, 0
.LBB0_2322:
	v_lshl_add_u64 v[96:97], s[4:5], 0, v[120:121]
	global_load_dwordx4 v[96:99], v[96:97], off
	s_and_b64 vcc, exec, s[24:25]
	s_mov_b64 s[0:1], -1
	s_cbranch_vccnz .LBB0_2332
	s_and_b64 vcc, exec, s[26:27]
	s_cbranch_vccnz .LBB0_2329
	s_and_b64 vcc, exec, s[10:11]
	s_cbranch_vccnz .LBB0_2326
	v_readlane_b32 s0, v253, 59
	s_add_u32 s4, s59, s0
	s_addc_u32 s5, s62, 0
	s_mov_b64 s[0:1], 0
.LBB0_2326:
	s_andn2_b64 vcc, exec, s[0:1]
	s_cbranch_vccnz .LBB0_2328
	s_add_u32 s0, s63, s69
	s_addc_u32 s1, s66, 0
	s_add_u32 s4, s0, 0xa3f4000
	s_addc_u32 s5, s1, 0

.LBB0_2332:
	s_andn2_b64 vcc, exec, s[0:1]
	s_cbranch_vccnz .LBB0_2334
	s_add_u32 s0, s60, s69
	s_addc_u32 s1, s67, 0
	s_add_u32 s4, s0, 0x73fc000
	s_addc_u32 s5, s1, 0
.LBB0_2334:
	v_lshl_add_u64 v[100:101], s[4:5], 0, v[120:121]
	global_load_dwordx4 v[100:103], v[100:101], off
	s_and_b64 vcc, exec, s[28:29]
	s_mov_b64 s[0:1], -1
	s_cbranch_vccnz .LBB0_2340
	s_and_b64 vcc, exec, s[14:15]
	s_cbranch_vccnz .LBB0_2337
	s_add_u32 s4, s59, s94
	s_addc_u32 s5, s62, 0
	s_mov_b64 s[0:1], 0
.LBB0_2337:
	s_andn2_b64 vcc, exec, s[0:1]
	s_cbranch_vccnz .LBB0_2339
	s_add_u32 s0, s63, s87
	s_addc_u32 s1, s66, 0
	s_add_u32 s4, s0, 0xa3f4000
	s_addc_u32 s5, s1, 0

.LBB0_2340:
	s_andn2_b64 vcc, exec, s[0:1]
	s_cbranch_vccnz .LBB0_2342
	s_add_u32 s0, s60, s87
	s_addc_u32 s1, s67, 0
	s_add_u32 s4, s0, 0x193f8000
	s_addc_u32 s5, s1, 0
.LBB0_2342:
	v_lshl_add_u64 v[104:105], s[4:5], 0, v[120:121]
	global_load_dwordx4 v[104:107], v[104:105], off
	s_and_b64 vcc, exec, s[30:31]
	s_mov_b64 s[0:1], -1
	s_cbranch_vccnz .LBB0_2348
	s_and_b64 vcc, exec, s[16:17]
	s_cbranch_vccnz .LBB0_2345
	s_add_u32 s4, s59, s36
	s_addc_u32 s5, s62, 0
	s_mov_b64 s[0:1], 0
.LBB0_2345:
	s_andn2_b64 vcc, exec, s[0:1]
	s_cbranch_vccnz .LBB0_2347
	s_add_u32 s0, s63, s95
	s_addc_u32 s1, s66, 0
	s_add_u32 s4, s0, 0xa3f4000
	s_addc_u32 s5, s1, 0

.LBB0_2350:
	s_add_u32 s0, s63, s37
	s_addc_u32 s1, s66, 0
	v_lshl_add_u64 v[108:109], s[4:5], 0, v[120:121]
	s_add_u32 s4, s0, 0xa3f4000
	s_addc_u32 s5, s1, 0
	s_add_u32 s60, s59, s40
	s_addc_u32 s67, s62, 0
	s_and_b64 s[0:1], s[84:85], exec
	s_cselect_b32 s1, s5, s67
	s_cselect_b32 s0, s4, s60
	v_lshl_add_u64 v[112:113], s[0:1], 0, v[120:121]
	s_add_u32 s0, s63, s41
	s_addc_u32 s1, s66, 0
	s_add_u32 s4, s0, 0xa3f4000
	s_addc_u32 s5, s1, 0
	s_add_u32 s59, s59, s97
	s_addc_u32 s60, s62, 0
	s_and_b64 s[0:1], s[92:93], exec
	s_cselect_b32 s1, s5, s60
	s_cselect_b32 s0, s4, s59
	v_lshl_add_u64 v[116:117], s[0:1], 0, v[120:121]
	s_lshl_b64 s[0:1], s[38:39], 2
	s_add_u32 s0, s54, s0
	s_addc_u32 s1, s55, s1
	global_load_dwordx4 v[108:111], v[108:109], off
	s_nop 0
	global_load_dwordx4 v[112:115], v[112:113], off
	s_nop 0
	global_load_dwordx4 v[116:119], v[116:117], off
	s_nop 0
	global_load_dword v129, v121, s[0:1]
